# speedup vs baseline: 1.0055x; 1.0036x over previous
; #define LAS __attribute__((address_space(3)))
; template <int LDQ, int LDK, int LDV, int LDO>
; __device__ __forceinline__ void attn256_body(const int tid, const bf16_t* __restrict__ Qb, const bf16_t* __restrict__ Kh, const bf16_t* __restrict__ Vh, bf16_t* __restrict__ Ob, int seq, char* lds, LAS unsigned char* ldsl) {
;     ...
;     unsigned kof[2], vof[4];
; #pragma unroll
;     for (int i = 0; i < 2; ++i) { const int q = (i * 8 + wid) * 64 + lane, row = q >> 4, chunk = (q & 15) ^ (row & 7); kof[i] = (unsigned)(row * LDK + chunk * 8) * 2u; }
; #pragma unroll
;     for (int i = 0; i < 4; ++i) { const int q = (i * 8 + wid) * 64 + lane, half = q >> 10, qq = q & 1023, sub = qq >> 5, kk = (sub >> 2) * 8 + ((qq >> 2) & 7), c = (sub & 3) * 32 + (qq & 3) * 8;
;         const int k = (kk & ~0xC) | ((kk & 4) << 1) | ((kk & 8) >> 1); vof[i] = (unsigned)(k * LDV + half * 128 + c) * 2u; }
;     ...
;     A2_ISSUE(0, 0);
; __device__ __forceinline__ void mix_phase(const int tid0, const P& p, int l, char* lds, const int per_q, const int cl) {
;     ...
;         __syncthreads();
;         const int item = *sitem;
;         __syncthreads();
;         if (item < 0) break;
;         const int xq = item >> 9, idx = item & 511;
;         if (idx < 12) { mlstm_item(tid, p, xq * 12 + idx, lds); }
;         else if (idx >= 108) {
;             const int t = xq * 258 + (idx - 108);
;             if (t < CT_UP) convert_tile(tid, (float*)lds, p.in[18] + (size_t)cl * DM * DFF, p.in[19] + (size_t)cl * DM * DFF, p.in[17] + (size_t)cl * DM, (bf16_t*)(p.ws + WS_WUP2), DM, DFF, 1, t);
;             else convert_tile(tid, (float*)lds, p.in[20] + (size_t)cl * DFF * DM, nullptr, nullptr, (bf16_t*)(p.ws + WS_WDN2), DFF, DM, 0, t - CT_UP);
;             __syncthreads();
;         }
;         else {
;             const int g = xq * 6 + ((idx - 12) >> 4), qblk = (idx - 12) & 15, comp = g & 1, head = (g >> 1) & 3, b = g >> 3;
;             const bf16_t* Q = qka + (size_t)(b * SEQ + qblk * 256) * 2048 + head * 256 + comp * 128;
;             const bf16_t* Kp = qka + (size_t)(b * SEQ) * 2048 + 1024 + head * 256 + comp * 128;
;             const bf16_t* Vp = z + (size_t)(b * SEQ) * ZLD + 6144 + head * 256;
;             bf16_t* O = z + (size_t)(b * SEQ + qblk * 256) * ZLD + 4096 + comp * 1024 + head * 256;
;             attn256_body<2048, 2048, ZLD, ZLD>(tid, Q, Kp, Vp, O, SEQ, lds, (LAS unsigned char*)lds);
.LBB0_130:
	s_or_b64 exec, exec, s[0:1]
	v_mov_b32_e32 v0, s33
	s_waitcnt lgkmcnt(0)
	s_barrier
	ds_read_b32 v0, v0
	s_waitcnt lgkmcnt(0)
	s_barrier
	v_cmp_gt_i32_e32 vcc, 0, v0
	v_readfirstlane_b32 s8, v0
	s_cbranch_vccnz .LBB0_142
	s_lshr_b32 s9, s8, 9
	s_and_b32 s14, s8, 0x1ff
	s_cmp_gt_u32 s14, 11
	s_mov_b64 s[0:1], -1
	s_cbranch_scc0 .LBB0_155
	s_cmpk_lt_u32 s14, 0x6c
	s_cbranch_scc0 .LBB0_146
	s_add_i32 s1, s14, -12
	s_mul_i32 s0, s9, 6
	s_lshr_b32 s4, s1, 4
	s_add_i32 s25, s4, s0
	s_lshl_b32 s0, s25, 9
	s_and_b32 s4, s0, 0x7ffff000
	s_lshl_b32 s0, s1, 8
	s_and_b32 s0, s0, 0xf00
	s_or_b32 s30, s4, s0
	s_bfe_u32 s15, s1, 0x10004
	s_lshl_b64 s[0:1], s[30:31], 12
	s_add_u32 s0, s54, s0
	s_addc_u32 s1, s67, s1
	s_lshl_b32 s5, s25, 7
	s_and_b32 s16, s5, 0x300
	s_lshl_b32 s17, s16, 1
	s_add_u32 s0, s0, s17
	s_addc_u32 s1, s1, 0
	s_lshl_b32 s24, s15, 8
	s_add_u32 s0, s0, s24
	s_mov_b32 s5, s31
	s_addc_u32 s1, s1, 0
	s_lshl_b64 s[6:7], s[4:5], 12
	s_add_u32 s5, s54, s6
	s_addc_u32 s21, s67, s7
	s_add_u32 s5, s5, s17
	s_addc_u32 s21, s21, 0
	s_add_u32 s22, s5, s24
	s_addc_u32 s23, s21, 0
	s_mul_i32 s36, s4, 0x3800
	s_mul_hi_u32 s28, s4, 0x3800
	s_add_u32 s4, s93, s36
	v_readfirstlane_b32 s21, v208
	s_addc_u32 s5, s66, s28
	s_movk_i32 s38, 0xffc0
	v_mov_b32_e32 v0, s21
	s_add_u32 s4, s4, s17
	v_bfi_b32 v2, s38, v0, v209
	s_addc_u32 s5, s5, 0
	v_and_b32_e32 v3, 15, v209
	v_ashrrev_i32_e32 v0, 4, v2
	v_add_u32_e32 v2, 0x200, v2
	s_add_u32 s4, s4, 0x3000
	v_bitop3_b32 v4, v0, v3, 15 bitop3:0x6c
	v_lshlrev_b32_e32 v0, 12, v0
	v_ashrrev_i32_e32 v2, 4, v2
	s_addc_u32 s5, s5, 0
	s_and_b32 s37, s21, 0xffffffc0
	v_lshl_or_b32 v0, v4, 4, v0
	v_bitop3_b32 v3, v2, v3, 15 bitop3:0x6c
	v_lshlrev_b32_e32 v2, 12, v2
	v_lshrrev_b32_e32 v4, 1, v208
	s_lshr_b32 s46, s21, 5
	v_lshl_or_b32 v2, v3, 4, v2
	v_bfe_u32 v3, v208, 2, 2
	v_and_b32_e32 v4, 8, v4
	s_and_b32 s46, s46, 4
	s_add_i32 s47, s37, 0x200
	v_lshlrev_b32_e32 v8, 3, v209
	v_or3_b32 v3, v4, v3, s46
	s_lshr_b32 s48, s47, 4
	s_lshl_b32 s17, s37, 2
	s_and_b32 s38, s21, 64
	v_and_b32_e32 v7, 32, v209
	v_and_b32_e32 v9, 24, v8
	s_lshr_b32 s46, s21, 4
	v_and_or_b32 v12, s48, 48, v3
	s_ashr_i32 s47, s47, 3
	s_add_i32 s48, s21, 0x400
	s_addk_i32 s37, 0x600
	v_or3_b32 v4, v9, v7, s38
	v_and_or_b32 v10, s46, 48, v3
	s_ashr_i32 s46, s21, 3
	s_and_b32 s47, s47, 0xffffff80
	s_ashr_i32 s48, s48, 3
	s_lshr_b32 s49, s37, 4
	s_ashr_i32 s37, s37, 3
	s_and_b32 s46, s46, 0xffffff80
	v_mul_u32_u24_e32 v13, 0x1c00, v12
	v_or_b32_e32 v14, s47, v4
	s_and_b32 s48, s48, 0xffffff80
	v_and_or_b32 v15, s49, 48, v3
	s_and_b32 s49, s37, 0xffffff80
	s_ashr_i32 s37, s21, 6
	v_mul_u32_u24_e32 v5, 0x1c00, v10
	v_or_b32_e32 v11, s46, v4
	v_add_lshl_u32 v13, v14, v13, 1
	v_or_b32_e32 v14, s48, v4
	v_mul_u32_u24_e32 v3, 0x1c00, v15
	v_or_b32_e32 v4, s49, v4
	s_lshl_b32 s21, s37, 10
	v_add_lshl_u32 v11, v11, v5, 1
	v_add_lshl_u32 v14, v14, v5, 1
	v_add_lshl_u32 v16, v4, v3, 1
	s_add_i32 s21, s21, 0
	v_lshl_add_u64 v[4:5], s[22:23], 0, v[0:1]
	s_mov_b64 s[56:57], 0x800
	v_lshl_add_u64 v[4:5], v[4:5], 0, s[56:57]
	s_mov_b32 m0, s21
	v_mov_b32_e32 v3, v1
	global_load_lds_dwordx4 v[4:5], off
	v_lshl_add_u64 v[4:5], s[22:23], 0, v[2:3]
	v_and_b32_e32 v211, 31, v209
	v_lshl_add_u64 v[4:5], v[4:5], 0, s[56:57]
	s_add_i32 m0, s21, 0x2000
	s_lshl_b32 s22, s37, 5
	global_load_lds_dwordx4 v[4:5], off
	s_add_i32 m0, s21, 0x8000
	v_or_b32_e32 v4, s22, v211
	global_load_lds_dwordx4 v11, s[4:5]
	s_add_i32 m0, s21, 0xa000
	v_ashrrev_i32_e32 v5, 31, v4
	v_bfe_u32 v210, v209, 5, 1
	global_load_lds_dwordx4 v13, s[4:5]
	s_add_i32 m0, s21, 0xc000
	v_lshlrev_b64 v[4:5], 12, v[4:5]
	global_load_lds_dwordx4 v14, s[4:5]
	s_add_i32 m0, s21, 0xe000
	v_lshl_add_u64 v[4:5], s[0:1], 0, v[4:5]
	v_lshlrev_b32_e32 v194, 4, v210
	v_mov_b32_e32 v195, v1
	global_load_lds_dwordx4 v16, s[4:5]
	v_lshl_add_u64 v[4:5], v[4:5], 0, v[194:195]
	global_load_dwordx4 v[162:165], v[4:5], off
	global_load_dwordx4 v[166:169], v[4:5], off offset:32
	global_load_dwordx4 v[170:173], v[4:5], off offset:64
	global_load_dwordx4 v[174:177], v[4:5], off offset:96
	global_load_dwordx4 v[178:181], v[4:5], off offset:128
	global_load_dwordx4 v[182:185], v[4:5], off offset:160
	global_load_dwordx4 v[186:189], v[4:5], off offset:192
	global_load_dwordx4 v[190:193], v[4:5], off offset:224
	v_lshlrev_b32_e32 v4, 4, v209
	v_and_b32_e32 v13, 0xf0, v4
	s_movk_i32 s0, 0x60
	v_bitop3_b32 v215, v194, v13, s0 bitop3:0x36
	s_movk_i32 s0, 0xa0
	s_add_i32 s17, s17, 0
	v_bitop3_b32 v218, v194, v13, s0 bitop3:0x36
	s_movk_i32 s0, 0xc0
	s_add_i32 s17, s17, 0x18000
	v_lshlrev_b32_e32 v11, 1, v209
	v_bitop3_b32 v219, v194, v13, s0 bitop3:0x36
	s_movk_i32 s0, 0xe0
	v_and_b32_e32 v11, 32, v11
	v_bitop3_b32 v220, v194, v13, s0 bitop3:0x36
	s_movk_i32 s0, 0x118
	s_cmp_lg_u32 0, -1
	v_and_b32_e32 v5, 0xc0, v4
	v_xor_b32_e32 v212, v194, v13
	v_and_or_b32 v4, v8, s0, v11
	s_cselect_b32 s0, 0, 0
	s_add_i32 s0, s0, 0x8000
	v_add3_u32 v221, v5, s0, v4
	s_lshl_b32 s0, s25, 8
	s_or_b32 s25, s38, s46
	v_mov_b32_e32 v4, s25
	s_movk_i32 s46, 0x1c00
	s_and_b32 s0, s0, 0x600
	v_mad_u32_u24 v4, v10, s46, v4
	v_readlane_b32 s25, v255, 17
	v_or3_b32 v4, v4, v7, v9
	s_add_u32 s36, s25, s36
	v_lshlrev_b32_e32 v4, 1, v4
	v_mov_b32_e32 v5, v1
	s_addc_u32 s37, s65, s28
	s_or_b32 s25, s38, s47
	v_lshl_add_u64 v[196:197], s[36:37], 0, v[4:5]
	v_mov_b32_e32 v4, s25
	v_mad_u32_u24 v4, v12, s46, v4
	v_or3_b32 v4, v4, v7, v9
	v_lshlrev_b32_e32 v4, 1, v4
	s_or_b32 s25, s38, s48
	v_lshl_add_u64 v[198:199], s[36:37], 0, v[4:5]
	v_mov_b32_e32 v4, s25
	v_mad_u32_u24 v4, v10, s46, v4
	v_or3_b32 v4, v4, v7, v9
	v_lshlrev_b32_e32 v4, 1, v4
	s_or_b32 s25, s38, s49
; __device__ __forceinline__ int v_rd_base(int lane) { return ((lane & 3) << 3) | (((lane >> 2) & 3) << 6) | (((lane >> 4) & 1) << 5) | (((lane >> 5) & 1) << 8); }
; template <int LDQ, int LDK, int LDV, int LDO>
; __device__ __forceinline__ void attn256_body(const int tid, const bf16_t* __restrict__ Qb, const bf16_t* __restrict__ Kh, const bf16_t* __restrict__ Vh, bf16_t* __restrict__ Ob, int seq, char* lds, LAS unsigned char* ldsl) {
;     ...
;     float m_reg = -1e30f, l_reg = 0; f32x16 o[8] = {}; bf16x8 qr[8];
;     unsigned kof[2], vof[4];
; #pragma unroll
;     for (int i = 0; i < 2; ++i) { const int q = (i * 8 + wid) * 64 + lane, row = q >> 4, chunk = (q & 15) ^ (row & 7); kof[i] = (unsigned)(row * LDK + chunk * 8) * 2u; }
; #pragma unroll
;     for (int i = 0; i < 4; ++i) { const int q = (i * 8 + wid) * 64 + lane, half = q >> 10, qq = q & 1023, sub = qq >> 5, kk = (sub >> 2) * 8 + ((qq >> 2) & 7), c = (sub & 3) * 32 + (qq & 3) * 8;
;         const int k = (kk & ~0xC) | ((kk & 4) << 1) | ((kk & 8) >> 1); vof[i] = (unsigned)(k * LDV + half * 128 + c) * 2u; }
;     ...
;     A2_ISSUE(0, 0);
;     { const bf16_t* Qw = Qb + (long)(wid * 32 + r32) * LDQ + hi * 8;
; #pragma unroll
;       for (int d0 = 0; d0 < 8; ++d0) qr[d0] = *reinterpret_cast<const bf16x8*>(Qw + d0 * 16); }
;     const int vb0 = (int)(uintptr_t)(lds + A2_VOFF) + v_rd_base(lane);
;     const int NT = seq / 64;
;     constexpr float C = ATT_SCALE * 1.4426950408889634f;
;     for (int j = 0; j < NT; ++j) {
;         const int b = j & 1;
;         asm volatile("s_waitcnt vmcnt(0)" ::: "memory"); __builtin_amdgcn_s_barrier(); asm volatile("" ::: "memory");
;         if (j + 1 < NT) A2_ISSUE(j + 1, b ^ 1);
;         f32x16 p0, p1;
;         qkt(p0, p1, lds + A2_KOFF + b * 16384, qr, r32, hi);
	v_lshl_add_u64 v[200:201], s[36:37], 0, v[4:5]
	v_mov_b32_e32 v4, s25
	v_mad_u32_u24 v4, v15, s46, v4
	s_or_b32 s6, s6, s24
	v_or3_b32 v4, v4, v7, v9
	s_add_u32 s6, s92, s6
	v_and_b32_e32 v6, 63, v209
	v_lshlrev_b32_e32 v4, 1, v4
	s_addc_u32 s7, s51, s7
	v_mov_b32_e32 v14, v1
	v_mov_b32_e32 v15, v1
	v_bitop3_b32 v213, v194, v13, 32 bitop3:0x36
	v_bitop3_b32 v214, v194, v13, 64 bitop3:0x36
	v_bitop3_b32 v216, v194, v13, s88 bitop3:0x36
	v_cmp_gt_u32_e64 s[4:5], 32, v6
	v_lshl_add_u64 v[202:203], s[36:37], 0, v[4:5]
	v_lshl_add_u64 v[204:205], s[6:7], 0, v[2:3]
	v_lshl_add_u64 v[206:207], s[6:7], 0, v[0:1]
	v_mov_b32_e32 v0, v1
	v_mov_b32_e32 v2, v1
	v_mov_b32_e32 v4, v1
	v_mov_b32_e32 v6, v1
	v_mov_b32_e32 v7, v1
	v_mov_b32_e32 v8, v1
	v_mov_b32_e32 v9, v1
	v_mov_b32_e32 v10, v1
	v_mov_b32_e32 v11, v1
	v_mov_b32_e32 v12, v1
	v_mov_b32_e32 v13, v1
	v_mov_b64_e32 v[128:129], v[14:15]
	v_mov_b64_e32 v[112:113], v[14:15]
	v_mov_b64_e32 v[96:97], v[14:15]
	v_mov_b64_e32 v[80:81], v[14:15]
	v_mov_b64_e32 v[64:65], v[14:15]
	v_mov_b64_e32 v[48:49], v[14:15]
	v_mov_b64_e32 v[32:33], v[14:15]
	v_mov_b64_e32 v[126:127], v[12:13]
	v_mov_b64_e32 v[124:125], v[10:11]
	v_mov_b64_e32 v[122:123], v[8:9]
	v_mov_b64_e32 v[120:121], v[6:7]
	v_mov_b64_e32 v[118:119], v[4:5]
	v_mov_b64_e32 v[116:117], v[2:3]
	v_mov_b64_e32 v[114:115], v[0:1]
	v_mov_b64_e32 v[110:111], v[12:13]
	v_mov_b64_e32 v[108:109], v[10:11]
	v_mov_b64_e32 v[106:107], v[8:9]
	v_mov_b64_e32 v[104:105], v[6:7]
	v_mov_b64_e32 v[102:103], v[4:5]
	v_mov_b64_e32 v[100:101], v[2:3]
	v_mov_b64_e32 v[98:99], v[0:1]
	v_mov_b64_e32 v[94:95], v[12:13]
	v_mov_b64_e32 v[92:93], v[10:11]
	v_mov_b64_e32 v[90:91], v[8:9]
	v_mov_b64_e32 v[88:89], v[6:7]
	v_mov_b64_e32 v[86:87], v[4:5]
	v_mov_b64_e32 v[84:85], v[2:3]
	v_mov_b64_e32 v[82:83], v[0:1]
	v_mov_b64_e32 v[78:79], v[12:13]
	v_mov_b64_e32 v[76:77], v[10:11]
	v_mov_b64_e32 v[74:75], v[8:9]
	v_mov_b64_e32 v[72:73], v[6:7]
	v_mov_b64_e32 v[70:71], v[4:5]
	v_mov_b64_e32 v[68:69], v[2:3]
	v_mov_b64_e32 v[66:67], v[0:1]
	v_mov_b64_e32 v[62:63], v[12:13]
	v_mov_b64_e32 v[60:61], v[10:11]
	v_mov_b64_e32 v[58:59], v[8:9]
	v_mov_b64_e32 v[56:57], v[6:7]
	v_mov_b64_e32 v[54:55], v[4:5]
	v_mov_b64_e32 v[52:53], v[2:3]
	v_mov_b64_e32 v[50:51], v[0:1]
	v_mov_b64_e32 v[46:47], v[12:13]
	v_mov_b64_e32 v[44:45], v[10:11]
	v_mov_b64_e32 v[42:43], v[8:9]
	v_mov_b64_e32 v[40:41], v[6:7]
	v_mov_b64_e32 v[38:39], v[4:5]
	v_mov_b64_e32 v[36:37], v[2:3]
	v_mov_b64_e32 v[34:35], v[0:1]
	v_mov_b64_e32 v[30:31], v[12:13]
	v_mov_b64_e32 v[28:29], v[10:11]
	v_mov_b64_e32 v[26:27], v[8:9]
	v_mov_b64_e32 v[24:25], v[6:7]
	v_mov_b64_e32 v[22:23], v[4:5]
	v_mov_b64_e32 v[20:21], v[2:3]
	v_mov_b64_e32 v[18:19], v[0:1]
	v_mov_b64_e32 v[16:17], v[14:15]
	v_lshlrev_b32_e32 v195, 8, v211
	v_lshl_add_u32 v217, v211, 2, s17
	s_mov_b32 s23, 0
	s_mov_b32 s1, s31
	v_mov_b32_e32 v223, 0
	v_mov_b32_e32 v222, 0xf149f2ca
	v_mov_b64_e32 v[14:15], v[12:13]
	v_mov_b64_e32 v[12:13], v[10:11]
	v_mov_b64_e32 v[10:11], v[8:9]
	v_mov_b64_e32 v[8:9], v[6:7]
	v_mov_b64_e32 v[6:7], v[4:5]
	v_mov_b64_e32 v[4:5], v[2:3]
	v_mov_b64_e32 v[2:3], v[0:1]
	s_waitcnt vmcnt(0)
	v_add_u32_e32 v212, v212, v195
	v_add_u32_e32 v213, v213, v195
	v_add_u32_e32 v214, v214, v195
	v_add_u32_e32 v215, v215, v195
	v_add_u32_e32 v216, v216, v195
	v_add_u32_e32 v218, v218, v195
	v_add_u32_e32 v219, v219, v195
	v_add_u32_e32 v220, v220, v195
	v_subrev_u32_e32 v204, s6, v204
	v_subrev_u32_e32 v206, s6, v206
	v_subrev_u32_e32 v196, s36, v196
	v_subrev_u32_e32 v198, s36, v198
	v_subrev_u32_e32 v200, s36, v200
	v_subrev_u32_e32 v202, s36, v202
	s_add_u32 s6, s6, s0
	s_addc_u32 s7, s7, s1
	s_add_u32 s36, s36, s0
	s_addc_u32 s37, s37, s1
.LBB0_134:
	s_waitcnt vmcnt(0)
	s_barrier
	s_add_i32 m0, s21, 0x4000
	ds_read_b128 v[224:227], v212
	global_load_lds_dwordx4 v206, s[6:7]
	s_add_i32 m0, s21, 0x6000
	ds_read_b128 v[228:231], v213
	global_load_lds_dwordx4 v204, s[6:7]
	s_add_i32 m0, s21, 0x10000
	ds_read_b128 v[232:235], v214
	global_load_lds_dwordx4 v196, s[36:37]
	s_add_i32 m0, s21, 0x12000
	ds_read_b128 v[236:239], v215
	global_load_lds_dwordx4 v198, s[36:37]
	s_add_i32 m0, s21, 0x14000
	ds_read_b128 v[244:247], v216
	global_load_lds_dwordx4 v200, s[36:37]
	s_add_i32 m0, s21, 0x16000
	ds_read_b128 v[248:251], v218
	global_load_lds_dwordx4 v202, s[36:37]
	s_waitcnt lgkmcnt(2)
	v_mfma_f32_32x32x16_bf16 v[130:145], v[224:227], v[162:165], 0
	ds_read_b128 v[224:227], v219
	v_mfma_f32_32x32x16_bf16 v[130:145], v[228:231], v[166:169], v[130:145]
	ds_read_b128 v[228:231], v220
	v_mfma_f32_32x32x16_bf16 v[130:145], v[232:235], v[170:173], v[130:145]
	ds_read_b128 v[232:235], v212 offset:8192
	v_mfma_f32_32x32x16_bf16 v[130:145], v[236:239], v[174:177], v[130:145]
	ds_read_b128 v[236:239], v213 offset:8192
	s_waitcnt lgkmcnt(2)
	v_mfma_f32_32x32x16_bf16 v[130:145], v[244:247], v[178:181], v[130:145]
	ds_read_b128 v[244:247], v214 offset:8192
	v_mfma_f32_32x32x16_bf16 v[130:145], v[248:251], v[182:185], v[130:145]
	ds_read_b128 v[248:251], v215 offset:8192
	v_mfma_f32_32x32x16_bf16 v[130:145], v[224:227], v[186:189], v[130:145]
	ds_read_b128 v[224:227], v216 offset:8192
	v_mfma_f32_32x32x16_bf16 v[130:145], v[228:231], v[190:193], v[130:145]
	ds_read_b128 v[228:231], v218 offset:8192
	s_waitcnt lgkmcnt(2)
	v_mfma_f32_32x32x16_bf16 v[146:161], v[232:235], v[162:165], 0
	ds_read_b128 v[232:235], v219 offset:8192
	v_mfma_f32_32x32x16_bf16 v[146:161], v[236:239], v[166:169], v[146:161]
	ds_read_b128 v[236:239], v220 offset:8192
	v_mfma_f32_32x32x16_bf16 v[146:161], v[244:247], v[170:173], v[146:161]
	ds_read_b64_tr_b16 v[244:245], v221 offset:0x0
	ds_read_b64_tr_b16 v[246:247], v221 offset:0x800
	v_mfma_f32_32x32x16_bf16 v[146:161], v[248:251], v[174:177], v[146:161]
	ds_read_b64_tr_b16 v[248:249], v221 offset:0x200
	ds_read_b64_tr_b16 v[250:251], v221 offset:0xa00
	v_max3_f32 v0, v130, v131, v132
	v_max3_f32 v0, v0, v133, v134
	s_waitcnt lgkmcnt(4)
; __device__ __forceinline__ int crow(int r, int hi) { return (r & 3) + 8 * (r >> 2) + 4 * hi; }
; template <int LDQ, int LDK, int LDV, int LDO>
; __device__ __forceinline__ void attn256_body(const int tid, const bf16_t* __restrict__ Qb, const bf16_t* __restrict__ Kh, const bf16_t* __restrict__ Vh, bf16_t* __restrict__ Ob, int seq, char* lds, LAS unsigned char* ldsl) {
;     ...
;         qkt(p0, p1, lds + A2_KOFF + b * 16384, qr, r32, hi);
;         float pmax = p0[0];
; #pragma unroll
;         for (int r = 1; r < 16; ++r) pmax = fmaxf(pmax, p0[r]);
; #pragma unroll
;         for (int r = 0; r < 16; ++r) pmax = fmaxf(pmax, p1[r]);
;         { auto rr = __builtin_amdgcn_permlane32_swap(__float_as_uint(pmax), __float_as_uint(pmax), false, false); pmax = fmaxf(__uint_as_float(rr[0]), __uint_as_float(rr[1])); }
;         float alpha = 1.f;
;         if (!__all(pmax - m_reg <= ATT_THR / ATT_SCALE)) { const float mn = fmaxf(m_reg, pmax); alpha = __builtin_amdgcn_exp2f((m_reg - mn) * C); m_reg = mn; }
;         const float mnC = -m_reg * C;
;         float ps = 0.f;
; #pragma unroll
;         for (int r = 0; r < 16; ++r) { p0[r] = __builtin_amdgcn_exp2f(fmaf(p0[r], C, mnC)); p1[r] = __builtin_amdgcn_exp2f(fmaf(p1[r], C, mnC)); ps += p0[r] + p1[r]; }
;         { auto rr = __builtin_amdgcn_permlane32_swap(__float_as_uint(ps), __float_as_uint(ps), false, false); ps = __uint_as_float(rr[0]) + __uint_as_float(rr[1]); }
;         l_reg = l_reg * alpha + ps;
;         bf16x8 pa0, pa1, pa2, pa3;
;         PK4(p0, 0, pa0); PK4(p0, 8, pa1); PK4(p1, 0, pa2); PK4(p1, 8, pa3);
;         if (__any(alpha < 1.f)) { if (hi == 0) al_l[r32] = alpha; asm volatile("s_waitcnt lgkmcnt(0)" ::: "memory");
; #pragma unroll
;             for (int r = 0; r < 16; ++r) { const float f = al_l[crow(r, hi)];
; #pragma unroll
;                 for (int d = 0; d < 8; ++d) o[d][r] *= f; } }
;         const int vb = vb0 + b * 32768;
;         pv256(o, vb, pa0, pa1, pa2, pa3);
	v_mfma_f32_32x32x16_bf16 v[146:161], v[224:227], v[178:181], v[146:161]
	ds_read_b64_tr_b16 v[224:225], v221 offset:0x400
	ds_read_b64_tr_b16 v[226:227], v221 offset:0xc00
	v_max3_f32 v0, v0, v135, v136
	v_max3_f32 v0, v0, v137, v138
	v_mfma_f32_32x32x16_bf16 v[146:161], v[228:231], v[182:185], v[146:161]
	ds_read_b64_tr_b16 v[228:229], v221 offset:0x600
	ds_read_b64_tr_b16 v[230:231], v221 offset:0xe00
	v_max3_f32 v0, v0, v139, v140
	v_max3_f32 v0, v0, v141, v142
	v_mfma_f32_32x32x16_bf16 v[146:161], v[232:235], v[186:189], v[146:161]
	ds_read_b64_tr_b16 v[232:233], v221 offset:0x4000
	ds_read_b64_tr_b16 v[234:235], v221 offset:0x4800
	v_max3_f32 v0, v0, v143, v144
	v_max_f32_e32 v0, v0, v145
	v_mfma_f32_32x32x16_bf16 v[146:161], v[236:239], v[190:193], v[146:161]
	ds_read_b64_tr_b16 v[236:237], v221 offset:0x4200
	ds_read_b64_tr_b16 v[238:239], v221 offset:0x4a00
	s_add_u32 s6, s6, 0x40000
	s_addc_u32 s7, s7, 0
	s_add_u32 s36, s36, 0xe0000
	s_addc_u32 s37, s37, 0
	s_add_i32 s23, s23, 1
	s_nop 4
	v_max3_f32 v0, v0, v146, v147
	v_max3_f32 v0, v0, v148, v149
	v_max3_f32 v0, v0, v150, v151
	v_max3_f32 v0, v0, v152, v153
	v_max3_f32 v0, v0, v154, v155
	v_max3_f32 v0, v0, v156, v157
	v_max3_f32 v0, v0, v158, v159
	v_max3_f32 v0, v0, v160, v161
	v_mov_b32_e32 v240, v0
	s_nop 1
	v_permlane32_swap_b32_e32 v0, v240
	v_max_f32_e32 v0, v0, v240
	v_sub_f32_e32 v240, v0, v222
	v_cmp_ge_f32_e32 vcc, 0x42b504f3, v240
	s_cmp_eq_u64 vcc, exec
	v_max_f32_e32 v0, v222, v0
	s_cselect_b64 vcc, -1, 0
	v_sub_f32_e32 v240, v222, v0
	v_cndmask_b32_e32 v222, v0, v222, vcc
	v_mul_f32_e32 v240, 0x3e0293ee, v240
	v_mul_f32_e32 v0, 0xbe0293ee, v222
	v_exp_f32_e32 v243, v240
	v_fmamk_f32 v130, v130, 0x3e0293ee, v0
	v_fmamk_f32 v131, v131, 0x3e0293ee, v0
	v_fmamk_f32 v132, v132, 0x3e0293ee, v0
	v_fmamk_f32 v133, v133, 0x3e0293ee, v0
	v_fmamk_f32 v134, v134, 0x3e0293ee, v0
	v_fmamk_f32 v135, v135, 0x3e0293ee, v0
	v_fmamk_f32 v136, v136, 0x3e0293ee, v0
	v_fmamk_f32 v137, v137, 0x3e0293ee, v0
	v_cndmask_b32_e64 v243, v243, 1.0, vcc
	v_cmp_gt_f32_e32 vcc, 1.0, v243
	s_cbranch_vccnz .Lattn_rescale_b0
.Lattn_resc_done_b0:
	v_exp_f32_e32 v130, v130
	v_exp_f32_e32 v131, v131
	v_exp_f32_e32 v132, v132
	v_exp_f32_e32 v133, v133
	v_exp_f32_e32 v134, v134
	v_exp_f32_e32 v135, v135
	v_exp_f32_e32 v136, v136
	v_exp_f32_e32 v137, v137
	v_add_f32_e32 v252, v130, v131
	v_cvt_pk_bf16_f32 v130, v130, v131
	v_add_f32_e32 v208, v132, v133
	v_cvt_pk_bf16_f32 v131, v132, v133
	v_add_f32_e32 v209, v134, v135
	v_cvt_pk_bf16_f32 v132, v134, v135
	v_add_f32_e32 v240, v136, v137
	v_cvt_pk_bf16_f32 v133, v136, v137
	s_nop 0
	v_permlane32_swap_b32_e32 v130, v132
	v_permlane32_swap_b32_e32 v131, v133
	v_add_f32_e32 v252, v252, v208
	v_add_f32_e32 v209, v209, v240
	v_add_f32_e32 v252, v252, v209
	s_waitcnt lgkmcnt(4)
	v_mfma_f32_32x32x16_bf16 v[114:129], v[130:133], v[244:247], v[114:129]
	v_fmamk_f32 v138, v138, 0x3e0293ee, v0
	v_exp_f32_e32 v138, v138
	v_fmamk_f32 v139, v139, 0x3e0293ee, v0
	v_exp_f32_e32 v139, v139
	ds_read_b64_tr_b16 v[244:245], v221 offset:0x4400
	ds_read_b64_tr_b16 v[246:247], v221 offset:0x4c00
	v_mfma_f32_32x32x16_bf16 v[98:113], v[130:133], v[248:251], v[98:113]
	v_add_f32_e32 v252, v252, v138
	v_fmamk_f32 v140, v140, 0x3e0293ee, v0
	v_exp_f32_e32 v140, v140
	v_add_f32_e32 v252, v252, v139
	v_fmamk_f32 v141, v141, 0x3e0293ee, v0
	ds_read_b64_tr_b16 v[248:249], v221 offset:0x4600
	ds_read_b64_tr_b16 v[250:251], v221 offset:0x4e00
	v_mfma_f32_32x32x16_bf16 v[82:97], v[130:133], v[224:227], v[82:97]
	v_exp_f32_e32 v141, v141
	v_add_f32_e32 v252, v252, v140
	v_fmamk_f32 v142, v142, 0x3e0293ee, v0
	v_exp_f32_e32 v142, v142
	ds_read_b64_tr_b16 v[224:225], v221 offset:0x1000
	ds_read_b64_tr_b16 v[226:227], v221 offset:0x1800
	v_mfma_f32_32x32x16_bf16 v[66:81], v[130:133], v[228:231], v[66:81]
	v_add_f32_e32 v252, v252, v141
	v_fmamk_f32 v143, v143, 0x3e0293ee, v0
	v_exp_f32_e32 v143, v143
	v_add_f32_e32 v252, v252, v142
	v_fmamk_f32 v144, v144, 0x3e0293ee, v0
	ds_read_b64_tr_b16 v[228:229], v221 offset:0x1200
	ds_read_b64_tr_b16 v[230:231], v221 offset:0x1a00
	s_waitcnt lgkmcnt(4)
	v_mfma_f32_32x32x16_bf16 v[50:65], v[130:133], v[232:235], v[50:65]
	v_exp_f32_e32 v144, v144
	v_add_f32_e32 v252, v252, v143
	v_fmamk_f32 v145, v145, 0x3e0293ee, v0
	v_exp_f32_e32 v145, v145
	ds_read_b64_tr_b16 v[232:233], v221 offset:0x1400
	ds_read_b64_tr_b16 v[234:235], v221 offset:0x1c00
	v_mfma_f32_32x32x16_bf16 v[34:49], v[130:133], v[236:239], v[34:49]
	v_add_f32_e32 v252, v252, v144
	v_cvt_pk_bf16_f32 v134, v138, v139
	v_add_f32_e32 v252, v252, v145
	v_cvt_pk_bf16_f32 v135, v140, v141
	v_cvt_pk_bf16_f32 v136, v142, v143
	v_cvt_pk_bf16_f32 v137, v144, v145
	ds_read_b64_tr_b16 v[236:237], v221 offset:0x1600
	ds_read_b64_tr_b16 v[238:239], v221 offset:0x1e00
	v_mfma_f32_32x32x16_bf16 v[18:33], v[130:133], v[244:247], v[18:33]
	s_nop 0
	v_permlane32_swap_b32_e32 v134, v136
	v_permlane32_swap_b32_e32 v135, v137
	v_fmamk_f32 v146, v146, 0x3e0293ee, v0
	v_exp_f32_e32 v146, v146
	ds_read_b64_tr_b16 v[244:245], v221 offset:0x5000
	ds_read_b64_tr_b16 v[246:247], v221 offset:0x5800
	v_mfma_f32_32x32x16_bf16 v[2:17], v[130:133], v[248:251], v[2:17]
	v_fmamk_f32 v147, v147, 0x3e0293ee, v0
	v_exp_f32_e32 v147, v147
	v_add_f32_e32 v252, v252, v146
	v_fmamk_f32 v148, v148, 0x3e0293ee, v0
	ds_read_b64_tr_b16 v[248:249], v221 offset:0x5200
	ds_read_b64_tr_b16 v[250:251], v221 offset:0x5a00
	s_waitcnt lgkmcnt(4)
; #define SBAR() __builtin_amdgcn_sched_barrier(0)
; #define PV_MMA(OD, R) do { OD = __builtin_amdgcn_mfma_f32_32x32x16_bf16(pa0, PKF(R[0], R[1]), OD, 0, 0, 0); OD = __builtin_amdgcn_mfma_f32_32x32x16_bf16(pa1, PKF(R[2], R[3]), OD, 0, 0, 0); \
;         OD = __builtin_amdgcn_mfma_f32_32x32x16_bf16(pa2, PKF(R[4], R[5]), OD, 0, 0, 0); OD = __builtin_amdgcn_mfma_f32_32x32x16_bf16(pa3, PKF(R[6], R[7]), OD, 0, 0, 0); SBAR(); } while (0)
; #define PV_W8() do { asm volatile("s_waitcnt lgkmcnt(8)" ::: "memory"); SBAR(); } while (0)
; __device__ __forceinline__ void pv256(f32x16* o, int vb, bf16x8 pa0, bf16x8 pa1, bf16x8 pa2, bf16x8 pa3) {
;     s16x4 ra[8], rb[8];
;     asm volatile("s_waitcnt lgkmcnt(0)" ::: "memory");
;     PV_RD8(0, 0, ra);
;     PV_RD8(1, 0, rb); PV_W8(); PV_MMA(o[0], ra);
;     PV_RD8(2, 0, ra); PV_W8(); PV_MMA(o[1], rb);
;     PV_RD8(3, 0, rb); PV_W8(); PV_MMA(o[2], ra);
;     PV_RD8(0, 16384, ra); PV_W8(); PV_MMA(o[3], rb);
;     PV_RD8(1, 16384, rb); PV_W8(); PV_MMA(o[4], ra);
;     PV_RD8(2, 16384, ra); PV_W8(); PV_MMA(o[5], rb);
;     PV_RD8(3, 16384, rb); PV_W8(); PV_MMA(o[6], ra);
;     asm volatile("s_waitcnt lgkmcnt(0)" ::: "memory"); SBAR(); PV_MMA(o[7], rb);
; }
	v_mfma_f32_32x32x16_bf16 v[114:129], v[134:137], v[224:227], v[114:129]
	v_exp_f32_e32 v148, v148
	v_add_f32_e32 v252, v252, v147
	v_fmamk_f32 v149, v149, 0x3e0293ee, v0
	v_exp_f32_e32 v149, v149
	ds_read_b64_tr_b16 v[224:225], v221 offset:0x5400
	ds_read_b64_tr_b16 v[226:227], v221 offset:0x5c00
	v_mfma_f32_32x32x16_bf16 v[98:113], v[134:137], v[228:231], v[98:113]
	v_add_f32_e32 v252, v252, v148
	v_fmamk_f32 v150, v150, 0x3e0293ee, v0
	v_exp_f32_e32 v150, v150
	v_add_f32_e32 v252, v252, v149
	v_fmamk_f32 v151, v151, 0x3e0293ee, v0
	ds_read_b64_tr_b16 v[228:229], v221 offset:0x5600
	ds_read_b64_tr_b16 v[230:231], v221 offset:0x5e00
	v_mfma_f32_32x32x16_bf16 v[82:97], v[134:137], v[232:235], v[82:97]
	v_exp_f32_e32 v151, v151
	v_add_f32_e32 v252, v252, v150
	v_fmamk_f32 v152, v152, 0x3e0293ee, v0
	v_exp_f32_e32 v152, v152
	ds_read_b64_tr_b16 v[232:233], v221 offset:0x2000
	ds_read_b64_tr_b16 v[234:235], v221 offset:0x2800
	v_mfma_f32_32x32x16_bf16 v[66:81], v[134:137], v[236:239], v[66:81]
	v_add_f32_e32 v252, v252, v151
	v_fmamk_f32 v153, v153, 0x3e0293ee, v0
	v_exp_f32_e32 v153, v153
	v_add_f32_e32 v252, v252, v152
	v_cvt_pk_bf16_f32 v138, v146, v147
	ds_read_b64_tr_b16 v[236:237], v221 offset:0x2200
	ds_read_b64_tr_b16 v[238:239], v221 offset:0x2a00
	s_waitcnt lgkmcnt(4)
	v_mfma_f32_32x32x16_bf16 v[50:65], v[134:137], v[244:247], v[50:65]
	v_add_f32_e32 v252, v252, v153
	v_cvt_pk_bf16_f32 v139, v148, v149
	v_cvt_pk_bf16_f32 v140, v150, v151
	v_cvt_pk_bf16_f32 v141, v152, v153
	s_nop 0
	v_permlane32_swap_b32_e32 v138, v140
	ds_read_b64_tr_b16 v[244:245], v221 offset:0x2400
	ds_read_b64_tr_b16 v[246:247], v221 offset:0x2c00
	v_mfma_f32_32x32x16_bf16 v[34:49], v[134:137], v[248:251], v[34:49]
	v_permlane32_swap_b32_e32 v139, v141
	v_fmamk_f32 v154, v154, 0x3e0293ee, v0
	v_exp_f32_e32 v154, v154
	v_fmamk_f32 v155, v155, 0x3e0293ee, v0
	ds_read_b64_tr_b16 v[248:249], v221 offset:0x2600
	ds_read_b64_tr_b16 v[250:251], v221 offset:0x2e00
	v_mfma_f32_32x32x16_bf16 v[18:33], v[134:137], v[224:227], v[18:33]
	v_exp_f32_e32 v155, v155
	v_add_f32_e32 v252, v252, v154
	v_fmamk_f32 v156, v156, 0x3e0293ee, v0
	v_exp_f32_e32 v156, v156
	ds_read_b64_tr_b16 v[224:225], v221 offset:0x6000
	ds_read_b64_tr_b16 v[226:227], v221 offset:0x6800
	v_mfma_f32_32x32x16_bf16 v[2:17], v[134:137], v[228:231], v[2:17]
	v_add_f32_e32 v252, v252, v155
	v_fmamk_f32 v157, v157, 0x3e0293ee, v0
	v_exp_f32_e32 v157, v157
	v_add_f32_e32 v252, v252, v156
	v_fmamk_f32 v158, v158, 0x3e0293ee, v0
	ds_read_b64_tr_b16 v[228:229], v221 offset:0x6200
	ds_read_b64_tr_b16 v[230:231], v221 offset:0x6a00
	s_waitcnt lgkmcnt(4)
	v_mfma_f32_32x32x16_bf16 v[114:129], v[138:141], v[232:235], v[114:129]
	v_exp_f32_e32 v158, v158
	v_add_f32_e32 v252, v252, v157
	v_fmamk_f32 v159, v159, 0x3e0293ee, v0
	v_exp_f32_e32 v159, v159
	ds_read_b64_tr_b16 v[232:233], v221 offset:0x6400
	ds_read_b64_tr_b16 v[234:235], v221 offset:0x6c00
	v_mfma_f32_32x32x16_bf16 v[98:113], v[138:141], v[236:239], v[98:113]
	v_add_f32_e32 v252, v252, v158
	v_fmamk_f32 v160, v160, 0x3e0293ee, v0
	v_exp_f32_e32 v160, v160
	v_add_f32_e32 v252, v252, v159
	v_fmamk_f32 v161, v161, 0x3e0293ee, v0
	ds_read_b64_tr_b16 v[236:237], v221 offset:0x6600
	ds_read_b64_tr_b16 v[238:239], v221 offset:0x6e00
	v_mfma_f32_32x32x16_bf16 v[82:97], v[138:141], v[244:247], v[82:97]
	v_exp_f32_e32 v161, v161
	v_add_f32_e32 v252, v252, v160
	v_cvt_pk_bf16_f32 v142, v154, v155
	v_add_f32_e32 v252, v252, v161
	v_cvt_pk_bf16_f32 v143, v156, v157
	ds_read_b64_tr_b16 v[244:245], v221 offset:0x3000
	ds_read_b64_tr_b16 v[246:247], v221 offset:0x3800
	v_mfma_f32_32x32x16_bf16 v[66:81], v[138:141], v[248:251], v[66:81]
	v_cvt_pk_bf16_f32 v144, v158, v159
	v_cvt_pk_bf16_f32 v145, v160, v161
	s_nop 0
	v_permlane32_swap_b32_e32 v142, v144
	v_permlane32_swap_b32_e32 v143, v145
	v_mov_b32_e32 v240, v252
	ds_read_b64_tr_b16 v[248:249], v221 offset:0x3200
	ds_read_b64_tr_b16 v[250:251], v221 offset:0x3a00
	s_waitcnt lgkmcnt(4)
	v_mfma_f32_32x32x16_bf16 v[50:65], v[138:141], v[224:227], v[50:65]
	s_nop 1
	v_permlane32_swap_b32_e32 v252, v240
	v_add_f32_e32 v240, v252, v240
	v_fma_f32 v223, v223, v243, v240
	ds_read_b64_tr_b16 v[224:225], v221 offset:0x3400
	ds_read_b64_tr_b16 v[226:227], v221 offset:0x3c00
	v_mfma_f32_32x32x16_bf16 v[34:49], v[138:141], v[228:231], v[34:49]
	ds_read_b64_tr_b16 v[228:229], v221 offset:0x3600
	ds_read_b64_tr_b16 v[230:231], v221 offset:0x3e00
	v_mfma_f32_32x32x16_bf16 v[18:33], v[138:141], v[232:235], v[18:33]
	ds_read_b64_tr_b16 v[232:233], v221 offset:0x7000
	ds_read_b64_tr_b16 v[234:235], v221 offset:0x7800
	v_mfma_f32_32x32x16_bf16 v[2:17], v[138:141], v[236:239], v[2:17]
	ds_read_b64_tr_b16 v[236:237], v221 offset:0x7200
	ds_read_b64_tr_b16 v[238:239], v221 offset:0x7a00
	s_waitcnt lgkmcnt(4)
	v_mfma_f32_32x32x16_bf16 v[114:129], v[142:145], v[244:247], v[114:129]
	ds_read_b64_tr_b16 v[244:245], v221 offset:0x7400
	ds_read_b64_tr_b16 v[246:247], v221 offset:0x7c00
	v_mfma_f32_32x32x16_bf16 v[98:113], v[142:145], v[248:251], v[98:113]
	ds_read_b64_tr_b16 v[248:249], v221 offset:0x7600
	ds_read_b64_tr_b16 v[250:251], v221 offset:0x7e00
	v_mfma_f32_32x32x16_bf16 v[82:97], v[142:145], v[224:227], v[82:97]
	v_mfma_f32_32x32x16_bf16 v[66:81], v[142:145], v[228:231], v[66:81]
	s_waitcnt lgkmcnt(0)
	v_mfma_f32_32x32x16_bf16 v[50:65], v[142:145], v[232:235], v[50:65]
	v_mfma_f32_32x32x16_bf16 v[34:49], v[142:145], v[236:239], v[34:49]
	v_mfma_f32_32x32x16_bf16 v[18:33], v[142:145], v[244:247], v[18:33]
	v_mfma_f32_32x32x16_bf16 v[2:17], v[142:145], v[248:251], v[2:17]
; template <int LDQ, int LDK, int LDV, int LDO>
; __device__ __forceinline__ void attn256_body(const int tid, const bf16_t* __restrict__ Qb, const bf16_t* __restrict__ Kh, const bf16_t* __restrict__ Vh, bf16_t* __restrict__ Ob, int seq, char* lds, LAS unsigned char* ldsl) {
;     ...
;     for (int j = 0; j < NT; ++j) {
;         const int b = j & 1;
;         asm volatile("s_waitcnt vmcnt(0)" ::: "memory"); __builtin_amdgcn_s_barrier(); asm volatile("" ::: "memory");
;         if (j + 1 < NT) A2_ISSUE(j + 1, b ^ 1);
;         f32x16 p0, p1;
;         qkt(p0, p1, lds + A2_KOFF + b * 16384, qr, r32, hi);
;         float pmax = p0[0];
; #pragma unroll
;         for (int r = 1; r < 16; ++r) pmax = fmaxf(pmax, p0[r]);
; #pragma unroll
;         for (int r = 0; r < 16; ++r) pmax = fmaxf(pmax, p1[r]);
;         { auto rr = __builtin_amdgcn_permlane32_swap(__float_as_uint(pmax), __float_as_uint(pmax), false, false); pmax = fmaxf(__uint_as_float(rr[0]), __uint_as_float(rr[1])); }
;         float alpha = 1.f;
;         if (!__all(pmax - m_reg <= ATT_THR / ATT_SCALE)) { const float mn = fmaxf(m_reg, pmax); alpha = __builtin_amdgcn_exp2f((m_reg - mn) * C); m_reg = mn; }
.Lattn_top_b1:
	s_waitcnt vmcnt(0)
	s_barrier
	ds_read_b128 v[224:227], v212 offset:16384
	ds_read_b128 v[228:231], v213 offset:16384
	ds_read_b128 v[232:235], v214 offset:16384
	ds_read_b128 v[236:239], v215 offset:16384
	ds_read_b128 v[244:247], v216 offset:16384
	ds_read_b128 v[248:251], v218 offset:16384
	s_cmp_eq_u32 s23, 63
	s_cbranch_scc1 .Lattn_nodma_b1
	s_mov_b32 m0, s21
	s_nop 0
	global_load_lds_dwordx4 v206, s[6:7]
	s_add_i32 m0, s21, 0x2000
	s_nop 0
	global_load_lds_dwordx4 v204, s[6:7]
	s_add_i32 m0, s21, 0x8000
	s_nop 0
	global_load_lds_dwordx4 v196, s[36:37]
	s_add_i32 m0, s21, 0xa000
	s_nop 0
	global_load_lds_dwordx4 v198, s[36:37]
	s_add_i32 m0, s21, 0xc000
	s_nop 0
	global_load_lds_dwordx4 v200, s[36:37]
	s_add_i32 m0, s21, 0xe000
	s_nop 0
	global_load_lds_dwordx4 v202, s[36:37]
.Lattn_nodma_b1:
	s_waitcnt lgkmcnt(2)
	v_mfma_f32_32x32x16_bf16 v[130:145], v[224:227], v[162:165], 0
	ds_read_b128 v[224:227], v219 offset:16384
	v_mfma_f32_32x32x16_bf16 v[130:145], v[228:231], v[166:169], v[130:145]
	ds_read_b128 v[228:231], v220 offset:16384
	v_mfma_f32_32x32x16_bf16 v[130:145], v[232:235], v[170:173], v[130:145]
	ds_read_b128 v[232:235], v212 offset:24576
	v_mfma_f32_32x32x16_bf16 v[130:145], v[236:239], v[174:177], v[130:145]
	ds_read_b128 v[236:239], v213 offset:24576
	s_waitcnt lgkmcnt(2)
	v_mfma_f32_32x32x16_bf16 v[130:145], v[244:247], v[178:181], v[130:145]
	ds_read_b128 v[244:247], v214 offset:24576
	v_mfma_f32_32x32x16_bf16 v[130:145], v[248:251], v[182:185], v[130:145]
	ds_read_b128 v[248:251], v215 offset:24576
	v_mfma_f32_32x32x16_bf16 v[130:145], v[224:227], v[186:189], v[130:145]
	ds_read_b128 v[224:227], v216 offset:24576
	v_mfma_f32_32x32x16_bf16 v[130:145], v[228:231], v[190:193], v[130:145]
	ds_read_b128 v[228:231], v218 offset:24576
	s_waitcnt lgkmcnt(2)
	v_mfma_f32_32x32x16_bf16 v[146:161], v[232:235], v[162:165], 0
	ds_read_b128 v[232:235], v219 offset:24576
	v_mfma_f32_32x32x16_bf16 v[146:161], v[236:239], v[166:169], v[146:161]
	ds_read_b128 v[236:239], v220 offset:24576
	v_mfma_f32_32x32x16_bf16 v[146:161], v[244:247], v[170:173], v[146:161]
	ds_read_b64_tr_b16 v[244:245], v221 offset:0x8000
	ds_read_b64_tr_b16 v[246:247], v221 offset:0x8800
	v_mfma_f32_32x32x16_bf16 v[146:161], v[248:251], v[174:177], v[146:161]
	ds_read_b64_tr_b16 v[248:249], v221 offset:0x8200
	ds_read_b64_tr_b16 v[250:251], v221 offset:0x8a00
	v_max3_f32 v0, v130, v131, v132
	v_max3_f32 v0, v0, v133, v134
	s_waitcnt lgkmcnt(4)
	v_mfma_f32_32x32x16_bf16 v[146:161], v[224:227], v[178:181], v[146:161]
	ds_read_b64_tr_b16 v[224:225], v221 offset:0x8400
	ds_read_b64_tr_b16 v[226:227], v221 offset:0x8c00
	v_max3_f32 v0, v0, v135, v136
	v_max3_f32 v0, v0, v137, v138
	v_mfma_f32_32x32x16_bf16 v[146:161], v[228:231], v[182:185], v[146:161]
	ds_read_b64_tr_b16 v[228:229], v221 offset:0x8600
	ds_read_b64_tr_b16 v[230:231], v221 offset:0x8e00
	v_max3_f32 v0, v0, v139, v140
	v_max3_f32 v0, v0, v141, v142
	v_mfma_f32_32x32x16_bf16 v[146:161], v[232:235], v[186:189], v[146:161]
	ds_read_b64_tr_b16 v[232:233], v221 offset:0xc000
	ds_read_b64_tr_b16 v[234:235], v221 offset:0xc800
	v_max3_f32 v0, v0, v143, v144
	v_max_f32_e32 v0, v0, v145
	v_mfma_f32_32x32x16_bf16 v[146:161], v[236:239], v[190:193], v[146:161]
	ds_read_b64_tr_b16 v[236:237], v221 offset:0xc200
	ds_read_b64_tr_b16 v[238:239], v221 offset:0xca00
	s_add_u32 s6, s6, 0x40000
	s_addc_u32 s7, s7, 0
	s_add_u32 s36, s36, 0xe0000
	s_addc_u32 s37, s37, 0
	s_add_i32 s23, s23, 1
	s_nop 4
	v_max3_f32 v0, v0, v146, v147
	v_max3_f32 v0, v0, v148, v149
	v_max3_f32 v0, v0, v150, v151
	v_max3_f32 v0, v0, v152, v153
	v_max3_f32 v0, v0, v154, v155
	v_max3_f32 v0, v0, v156, v157
	v_max3_f32 v0, v0, v158, v159
	v_max3_f32 v0, v0, v160, v161
	v_mov_b32_e32 v240, v0
	s_nop 1
	v_permlane32_swap_b32_e32 v0, v240
	v_max_f32_e32 v0, v0, v240
	v_sub_f32_e32 v240, v0, v222
	v_cmp_ge_f32_e32 vcc, 0x42b504f3, v240
	s_cmp_eq_u64 vcc, exec
	v_max_f32_e32 v0, v222, v0
	s_cselect_b64 vcc, -1, 0
	v_sub_f32_e32 v240, v222, v0
	v_cndmask_b32_e32 v222, v0, v222, vcc
	v_mul_f32_e32 v240, 0x3e0293ee, v240
	v_mul_f32_e32 v0, 0xbe0293ee, v222
	v_exp_f32_e32 v243, v240
	v_fmamk_f32 v130, v130, 0x3e0293ee, v0
	v_fmamk_f32 v131, v131, 0x3e0293ee, v0
	v_fmamk_f32 v132, v132, 0x3e0293ee, v0
	v_fmamk_f32 v133, v133, 0x3e0293ee, v0
	v_fmamk_f32 v134, v134, 0x3e0293ee, v0
	v_fmamk_f32 v135, v135, 0x3e0293ee, v0
	v_fmamk_f32 v136, v136, 0x3e0293ee, v0
	v_fmamk_f32 v137, v137, 0x3e0293ee, v0
	v_cndmask_b32_e64 v243, v243, 1.0, vcc
	v_cmp_gt_f32_e32 vcc, 1.0, v243
	s_cbranch_vccnz .Lattn_rescale_b1
; #define SBAR() __builtin_amdgcn_sched_barrier(0)
; #define PV_MMA(OD, R) do { OD = __builtin_amdgcn_mfma_f32_32x32x16_bf16(pa0, PKF(R[0], R[1]), OD, 0, 0, 0); OD = __builtin_amdgcn_mfma_f32_32x32x16_bf16(pa1, PKF(R[2], R[3]), OD, 0, 0, 0); \
;         OD = __builtin_amdgcn_mfma_f32_32x32x16_bf16(pa2, PKF(R[4], R[5]), OD, 0, 0, 0); OD = __builtin_amdgcn_mfma_f32_32x32x16_bf16(pa3, PKF(R[6], R[7]), OD, 0, 0, 0); SBAR(); } while (0)
; #define PV_W8() do { asm volatile("s_waitcnt lgkmcnt(8)" ::: "memory"); SBAR(); } while (0)
; __device__ __forceinline__ void pv256(f32x16* o, int vb, bf16x8 pa0, bf16x8 pa1, bf16x8 pa2, bf16x8 pa3) {
;     s16x4 ra[8], rb[8];
;     asm volatile("s_waitcnt lgkmcnt(0)" ::: "memory");
;     PV_RD8(0, 0, ra);
;     PV_RD8(1, 0, rb); PV_W8(); PV_MMA(o[0], ra);
;     PV_RD8(2, 0, ra); PV_W8(); PV_MMA(o[1], rb);
;     PV_RD8(3, 0, rb); PV_W8(); PV_MMA(o[2], ra);
;     PV_RD8(0, 16384, ra); PV_W8(); PV_MMA(o[3], rb);
;     PV_RD8(1, 16384, rb); PV_W8(); PV_MMA(o[4], ra);
;     PV_RD8(2, 16384, ra); PV_W8(); PV_MMA(o[5], rb);
;     PV_RD8(3, 16384, rb); PV_W8(); PV_MMA(o[6], ra);
;     asm volatile("s_waitcnt lgkmcnt(0)" ::: "memory"); SBAR(); PV_MMA(o[7], rb);
; }
; template <int LDQ, int LDK, int LDV, int LDO>
; __device__ __forceinline__ void attn256_body(const int tid, const bf16_t* __restrict__ Qb, const bf16_t* __restrict__ Kh, const bf16_t* __restrict__ Vh, bf16_t* __restrict__ Ob, int seq, char* lds, LAS unsigned char* ldsl) {
;     ...
;         float ps = 0.f;
; #pragma unroll
;         for (int r = 0; r < 16; ++r) { p0[r] = __builtin_amdgcn_exp2f(fmaf(p0[r], C, mnC)); p1[r] = __builtin_amdgcn_exp2f(fmaf(p1[r], C, mnC)); ps += p0[r] + p1[r]; }
;         { auto rr = __builtin_amdgcn_permlane32_swap(__float_as_uint(ps), __float_as_uint(ps), false, false); ps = __uint_as_float(rr[0]) + __uint_as_float(rr[1]); }
;         l_reg = l_reg * alpha + ps;
;         bf16x8 pa0, pa1, pa2, pa3;
;         PK4(p0, 0, pa0); PK4(p0, 8, pa1); PK4(p1, 0, pa2); PK4(p1, 8, pa3);
.Lattn_resc_done_b1:
	v_exp_f32_e32 v130, v130
	v_exp_f32_e32 v131, v131
	v_exp_f32_e32 v132, v132
	v_exp_f32_e32 v133, v133
	v_exp_f32_e32 v134, v134
	v_exp_f32_e32 v135, v135
	v_exp_f32_e32 v136, v136
	v_exp_f32_e32 v137, v137
	v_add_f32_e32 v252, v130, v131
	v_cvt_pk_bf16_f32 v130, v130, v131
	v_add_f32_e32 v208, v132, v133
	v_cvt_pk_bf16_f32 v131, v132, v133
	v_add_f32_e32 v209, v134, v135
	v_cvt_pk_bf16_f32 v132, v134, v135
	v_add_f32_e32 v240, v136, v137
	v_cvt_pk_bf16_f32 v133, v136, v137
	s_nop 0
	v_permlane32_swap_b32_e32 v130, v132
	v_permlane32_swap_b32_e32 v131, v133
	v_add_f32_e32 v252, v252, v208
	v_add_f32_e32 v209, v209, v240
	v_add_f32_e32 v252, v252, v209
	s_waitcnt lgkmcnt(4)
	v_mfma_f32_32x32x16_bf16 v[114:129], v[130:133], v[244:247], v[114:129]
	v_fmamk_f32 v138, v138, 0x3e0293ee, v0
	v_exp_f32_e32 v138, v138
	v_fmamk_f32 v139, v139, 0x3e0293ee, v0
	v_exp_f32_e32 v139, v139
	ds_read_b64_tr_b16 v[244:245], v221 offset:0xc400
	ds_read_b64_tr_b16 v[246:247], v221 offset:0xcc00
	v_mfma_f32_32x32x16_bf16 v[98:113], v[130:133], v[248:251], v[98:113]
	v_add_f32_e32 v252, v252, v138
	v_fmamk_f32 v140, v140, 0x3e0293ee, v0
	v_exp_f32_e32 v140, v140
	v_add_f32_e32 v252, v252, v139
	v_fmamk_f32 v141, v141, 0x3e0293ee, v0
	ds_read_b64_tr_b16 v[248:249], v221 offset:0xc600
	ds_read_b64_tr_b16 v[250:251], v221 offset:0xce00
	v_mfma_f32_32x32x16_bf16 v[82:97], v[130:133], v[224:227], v[82:97]
	v_exp_f32_e32 v141, v141
	v_add_f32_e32 v252, v252, v140
	v_fmamk_f32 v142, v142, 0x3e0293ee, v0
	v_exp_f32_e32 v142, v142
	ds_read_b64_tr_b16 v[224:225], v221 offset:0x9000
	ds_read_b64_tr_b16 v[226:227], v221 offset:0x9800
	v_mfma_f32_32x32x16_bf16 v[66:81], v[130:133], v[228:231], v[66:81]
	v_add_f32_e32 v252, v252, v141
	v_fmamk_f32 v143, v143, 0x3e0293ee, v0
	v_exp_f32_e32 v143, v143
	v_add_f32_e32 v252, v252, v142
	v_fmamk_f32 v144, v144, 0x3e0293ee, v0
	ds_read_b64_tr_b16 v[228:229], v221 offset:0x9200
	ds_read_b64_tr_b16 v[230:231], v221 offset:0x9a00
	s_waitcnt lgkmcnt(4)
	v_mfma_f32_32x32x16_bf16 v[50:65], v[130:133], v[232:235], v[50:65]
	v_exp_f32_e32 v144, v144
	v_add_f32_e32 v252, v252, v143
	v_fmamk_f32 v145, v145, 0x3e0293ee, v0
	v_exp_f32_e32 v145, v145
	ds_read_b64_tr_b16 v[232:233], v221 offset:0x9400
	ds_read_b64_tr_b16 v[234:235], v221 offset:0x9c00
	v_mfma_f32_32x32x16_bf16 v[34:49], v[130:133], v[236:239], v[34:49]
	v_add_f32_e32 v252, v252, v144
	v_cvt_pk_bf16_f32 v134, v138, v139
	v_add_f32_e32 v252, v252, v145
	v_cvt_pk_bf16_f32 v135, v140, v141
	v_cvt_pk_bf16_f32 v136, v142, v143
	v_cvt_pk_bf16_f32 v137, v144, v145
	ds_read_b64_tr_b16 v[236:237], v221 offset:0x9600
	ds_read_b64_tr_b16 v[238:239], v221 offset:0x9e00
	v_mfma_f32_32x32x16_bf16 v[18:33], v[130:133], v[244:247], v[18:33]
	s_nop 0
	v_permlane32_swap_b32_e32 v134, v136
	v_permlane32_swap_b32_e32 v135, v137
	v_fmamk_f32 v146, v146, 0x3e0293ee, v0
	v_exp_f32_e32 v146, v146
	ds_read_b64_tr_b16 v[244:245], v221 offset:0xd000
	ds_read_b64_tr_b16 v[246:247], v221 offset:0xd800
	v_mfma_f32_32x32x16_bf16 v[2:17], v[130:133], v[248:251], v[2:17]
	v_fmamk_f32 v147, v147, 0x3e0293ee, v0
	v_exp_f32_e32 v147, v147
	v_add_f32_e32 v252, v252, v146
	v_fmamk_f32 v148, v148, 0x3e0293ee, v0
	ds_read_b64_tr_b16 v[248:249], v221 offset:0xd200
	ds_read_b64_tr_b16 v[250:251], v221 offset:0xda00
	s_waitcnt lgkmcnt(4)
	v_mfma_f32_32x32x16_bf16 v[114:129], v[134:137], v[224:227], v[114:129]
	v_exp_f32_e32 v148, v148
	v_add_f32_e32 v252, v252, v147
	v_fmamk_f32 v149, v149, 0x3e0293ee, v0
	v_exp_f32_e32 v149, v149
	ds_read_b64_tr_b16 v[224:225], v221 offset:0xd400
	ds_read_b64_tr_b16 v[226:227], v221 offset:0xdc00
	v_mfma_f32_32x32x16_bf16 v[98:113], v[134:137], v[228:231], v[98:113]
	v_add_f32_e32 v252, v252, v148
	v_fmamk_f32 v150, v150, 0x3e0293ee, v0
	v_exp_f32_e32 v150, v150
	v_add_f32_e32 v252, v252, v149
	v_fmamk_f32 v151, v151, 0x3e0293ee, v0
	ds_read_b64_tr_b16 v[228:229], v221 offset:0xd600
	ds_read_b64_tr_b16 v[230:231], v221 offset:0xde00
	v_mfma_f32_32x32x16_bf16 v[82:97], v[134:137], v[232:235], v[82:97]
	v_exp_f32_e32 v151, v151
	v_add_f32_e32 v252, v252, v150
	v_fmamk_f32 v152, v152, 0x3e0293ee, v0
	v_exp_f32_e32 v152, v152
	ds_read_b64_tr_b16 v[232:233], v221 offset:0xa000
	ds_read_b64_tr_b16 v[234:235], v221 offset:0xa800
	v_mfma_f32_32x32x16_bf16 v[66:81], v[134:137], v[236:239], v[66:81]
	v_add_f32_e32 v252, v252, v151
	v_fmamk_f32 v153, v153, 0x3e0293ee, v0
	v_exp_f32_e32 v153, v153
	v_add_f32_e32 v252, v252, v152
	v_cvt_pk_bf16_f32 v138, v146, v147
	ds_read_b64_tr_b16 v[236:237], v221 offset:0xa200
	ds_read_b64_tr_b16 v[238:239], v221 offset:0xaa00
	s_waitcnt lgkmcnt(4)
	v_mfma_f32_32x32x16_bf16 v[50:65], v[134:137], v[244:247], v[50:65]
	v_add_f32_e32 v252, v252, v153
	v_cvt_pk_bf16_f32 v139, v148, v149
	v_cvt_pk_bf16_f32 v140, v150, v151
	v_cvt_pk_bf16_f32 v141, v152, v153
	s_nop 0
	v_permlane32_swap_b32_e32 v138, v140
	ds_read_b64_tr_b16 v[244:245], v221 offset:0xa400
	ds_read_b64_tr_b16 v[246:247], v221 offset:0xac00
	v_mfma_f32_32x32x16_bf16 v[34:49], v[134:137], v[248:251], v[34:49]
	v_permlane32_swap_b32_e32 v139, v141
	v_fmamk_f32 v154, v154, 0x3e0293ee, v0
	v_exp_f32_e32 v154, v154
	v_fmamk_f32 v155, v155, 0x3e0293ee, v0
	ds_read_b64_tr_b16 v[248:249], v221 offset:0xa600
	ds_read_b64_tr_b16 v[250:251], v221 offset:0xae00
	v_mfma_f32_32x32x16_bf16 v[18:33], v[134:137], v[224:227], v[18:33]
	v_exp_f32_e32 v155, v155
	v_add_f32_e32 v252, v252, v154
	v_fmamk_f32 v156, v156, 0x3e0293ee, v0
	v_exp_f32_e32 v156, v156
	ds_read_b64_tr_b16 v[224:225], v221 offset:0xe000
	ds_read_b64_tr_b16 v[226:227], v221 offset:0xe800
	v_mfma_f32_32x32x16_bf16 v[2:17], v[134:137], v[228:231], v[2:17]
	v_add_f32_e32 v252, v252, v155
	v_fmamk_f32 v157, v157, 0x3e0293ee, v0
	v_exp_f32_e32 v157, v157
	v_add_f32_e32 v252, v252, v156
	v_fmamk_f32 v158, v158, 0x3e0293ee, v0
	ds_read_b64_tr_b16 v[228:229], v221 offset:0xe200
	ds_read_b64_tr_b16 v[230:231], v221 offset:0xea00
	s_waitcnt lgkmcnt(4)
; __device__ __forceinline__ int crow(int r, int hi) { return (r & 3) + 8 * (r >> 2) + 4 * hi; }
; #define SBAR() __builtin_amdgcn_sched_barrier(0)
; #define PV_MMA(OD, R) do { OD = __builtin_amdgcn_mfma_f32_32x32x16_bf16(pa0, PKF(R[0], R[1]), OD, 0, 0, 0); OD = __builtin_amdgcn_mfma_f32_32x32x16_bf16(pa1, PKF(R[2], R[3]), OD, 0, 0, 0); \
;         OD = __builtin_amdgcn_mfma_f32_32x32x16_bf16(pa2, PKF(R[4], R[5]), OD, 0, 0, 0); OD = __builtin_amdgcn_mfma_f32_32x32x16_bf16(pa3, PKF(R[6], R[7]), OD, 0, 0, 0); SBAR(); } while (0)
; #define PV_W8() do { asm volatile("s_waitcnt lgkmcnt(8)" ::: "memory"); SBAR(); } while (0)
; __device__ __forceinline__ void pv256(f32x16* o, int vb, bf16x8 pa0, bf16x8 pa1, bf16x8 pa2, bf16x8 pa3) {
;     s16x4 ra[8], rb[8];
;     asm volatile("s_waitcnt lgkmcnt(0)" ::: "memory");
;     PV_RD8(0, 0, ra);
;     PV_RD8(1, 0, rb); PV_W8(); PV_MMA(o[0], ra);
;     PV_RD8(2, 0, ra); PV_W8(); PV_MMA(o[1], rb);
;     PV_RD8(3, 0, rb); PV_W8(); PV_MMA(o[2], ra);
;     PV_RD8(0, 16384, ra); PV_W8(); PV_MMA(o[3], rb);
;     PV_RD8(1, 16384, rb); PV_W8(); PV_MMA(o[4], ra);
;     PV_RD8(2, 16384, ra); PV_W8(); PV_MMA(o[5], rb);
;     PV_RD8(3, 16384, rb); PV_W8(); PV_MMA(o[6], ra);
;     asm volatile("s_waitcnt lgkmcnt(0)" ::: "memory"); SBAR(); PV_MMA(o[7], rb);
; }
; template <int LDQ, int LDK, int LDV, int LDO>
; __device__ __forceinline__ void attn256_body(const int tid, const bf16_t* __restrict__ Qb, const bf16_t* __restrict__ Kh, const bf16_t* __restrict__ Vh, bf16_t* __restrict__ Ob, int seq, char* lds, LAS unsigned char* ldsl) {
;     ...
;         { auto rr = __builtin_amdgcn_permlane32_swap(__float_as_uint(ps), __float_as_uint(ps), false, false); ps = __uint_as_float(rr[0]) + __uint_as_float(rr[1]); }
;         l_reg = l_reg * alpha + ps;
;         bf16x8 pa0, pa1, pa2, pa3;
;         PK4(p0, 0, pa0); PK4(p0, 8, pa1); PK4(p1, 0, pa2); PK4(p1, 8, pa3);
;         if (__any(alpha < 1.f)) { if (hi == 0) al_l[r32] = alpha; asm volatile("s_waitcnt lgkmcnt(0)" ::: "memory");
; #pragma unroll
;             for (int r = 0; r < 16; ++r) { const float f = al_l[crow(r, hi)];
; #pragma unroll
;                 for (int d = 0; d < 8; ++d) o[d][r] *= f; } }
	v_mfma_f32_32x32x16_bf16 v[114:129], v[138:141], v[232:235], v[114:129]
	v_exp_f32_e32 v158, v158
	v_add_f32_e32 v252, v252, v157
	v_fmamk_f32 v159, v159, 0x3e0293ee, v0
	v_exp_f32_e32 v159, v159
	ds_read_b64_tr_b16 v[232:233], v221 offset:0xe400
	ds_read_b64_tr_b16 v[234:235], v221 offset:0xec00
	v_mfma_f32_32x32x16_bf16 v[98:113], v[138:141], v[236:239], v[98:113]
	v_add_f32_e32 v252, v252, v158
	v_fmamk_f32 v160, v160, 0x3e0293ee, v0
	v_exp_f32_e32 v160, v160
	v_add_f32_e32 v252, v252, v159
	v_fmamk_f32 v161, v161, 0x3e0293ee, v0
	ds_read_b64_tr_b16 v[236:237], v221 offset:0xe600
	ds_read_b64_tr_b16 v[238:239], v221 offset:0xee00
	v_mfma_f32_32x32x16_bf16 v[82:97], v[138:141], v[244:247], v[82:97]
	v_exp_f32_e32 v161, v161
	v_add_f32_e32 v252, v252, v160
	v_cvt_pk_bf16_f32 v142, v154, v155
	v_add_f32_e32 v252, v252, v161
	v_cvt_pk_bf16_f32 v143, v156, v157
	ds_read_b64_tr_b16 v[244:245], v221 offset:0xb000
	ds_read_b64_tr_b16 v[246:247], v221 offset:0xb800
	v_mfma_f32_32x32x16_bf16 v[66:81], v[138:141], v[248:251], v[66:81]
	v_cvt_pk_bf16_f32 v144, v158, v159
	v_cvt_pk_bf16_f32 v145, v160, v161
	s_nop 0
	v_permlane32_swap_b32_e32 v142, v144
	v_permlane32_swap_b32_e32 v143, v145
	v_mov_b32_e32 v240, v252
	ds_read_b64_tr_b16 v[248:249], v221 offset:0xb200
	ds_read_b64_tr_b16 v[250:251], v221 offset:0xba00
	s_waitcnt lgkmcnt(4)
	v_mfma_f32_32x32x16_bf16 v[50:65], v[138:141], v[224:227], v[50:65]
	s_nop 1
	v_permlane32_swap_b32_e32 v252, v240
	v_add_f32_e32 v240, v252, v240
	v_fma_f32 v223, v223, v243, v240
	ds_read_b64_tr_b16 v[224:225], v221 offset:0xb400
	ds_read_b64_tr_b16 v[226:227], v221 offset:0xbc00
	v_mfma_f32_32x32x16_bf16 v[34:49], v[138:141], v[228:231], v[34:49]
	ds_read_b64_tr_b16 v[228:229], v221 offset:0xb600
	ds_read_b64_tr_b16 v[230:231], v221 offset:0xbe00
	v_mfma_f32_32x32x16_bf16 v[18:33], v[138:141], v[232:235], v[18:33]
	ds_read_b64_tr_b16 v[232:233], v221 offset:0xf000
	ds_read_b64_tr_b16 v[234:235], v221 offset:0xf800
	v_mfma_f32_32x32x16_bf16 v[2:17], v[138:141], v[236:239], v[2:17]
	ds_read_b64_tr_b16 v[236:237], v221 offset:0xf200
	ds_read_b64_tr_b16 v[238:239], v221 offset:0xfa00
	s_waitcnt lgkmcnt(4)
	v_mfma_f32_32x32x16_bf16 v[114:129], v[142:145], v[244:247], v[114:129]
	ds_read_b64_tr_b16 v[244:245], v221 offset:0xf400
	ds_read_b64_tr_b16 v[246:247], v221 offset:0xfc00
	v_mfma_f32_32x32x16_bf16 v[98:113], v[142:145], v[248:251], v[98:113]
	ds_read_b64_tr_b16 v[248:249], v221 offset:0xf600
	ds_read_b64_tr_b16 v[250:251], v221 offset:0xfe00
	v_mfma_f32_32x32x16_bf16 v[82:97], v[142:145], v[224:227], v[82:97]
	v_mfma_f32_32x32x16_bf16 v[66:81], v[142:145], v[228:231], v[66:81]
	s_waitcnt lgkmcnt(0)
	v_mfma_f32_32x32x16_bf16 v[50:65], v[142:145], v[232:235], v[50:65]
	v_mfma_f32_32x32x16_bf16 v[34:49], v[142:145], v[236:239], v[34:49]
	v_mfma_f32_32x32x16_bf16 v[18:33], v[142:145], v[244:247], v[18:33]
	v_mfma_f32_32x32x16_bf16 v[2:17], v[142:145], v[248:251], v[2:17]
	s_cmp_eq_u32 s23, 64
	s_cbranch_scc0 .LBB0_134
	v_mov_b32_e32 v146, v223
	s_branch .LBB0_143
.Lattn_rescale_b0:
	s_and_saveexec_b64 vcc, s[4:5]
	ds_write_b32 v217, v243 offset:128
	s_or_b64 exec, exec, vcc
	s_waitcnt lgkmcnt(0)
	v_add_u32_e32 v240, s17, v194
	ds_read_b128 v[224:227], v240 offset:128
	ds_read_b128 v[228:231], v240 offset:160
	ds_read_b128 v[232:235], v240 offset:192
	ds_read_b128 v[236:239], v240 offset:224
	s_waitcnt lgkmcnt(0)
	v_pk_mul_f32 v[114:115], v[114:115], v[224:225]
	v_pk_mul_f32 v[116:117], v[116:117], v[226:227]
	v_pk_mul_f32 v[118:119], v[118:119], v[228:229]
	v_pk_mul_f32 v[120:121], v[120:121], v[230:231]
	v_pk_mul_f32 v[122:123], v[122:123], v[232:233]
	v_pk_mul_f32 v[124:125], v[124:125], v[234:235]
	v_pk_mul_f32 v[126:127], v[126:127], v[236:237]
	v_pk_mul_f32 v[128:129], v[128:129], v[238:239]
	v_pk_mul_f32 v[98:99], v[98:99], v[224:225]
	v_pk_mul_f32 v[100:101], v[100:101], v[226:227]
	v_pk_mul_f32 v[102:103], v[102:103], v[228:229]
	v_pk_mul_f32 v[104:105], v[104:105], v[230:231]
	v_pk_mul_f32 v[106:107], v[106:107], v[232:233]
	v_pk_mul_f32 v[108:109], v[108:109], v[234:235]
	v_pk_mul_f32 v[110:111], v[110:111], v[236:237]
	v_pk_mul_f32 v[112:113], v[112:113], v[238:239]
	v_pk_mul_f32 v[82:83], v[82:83], v[224:225]
	v_pk_mul_f32 v[84:85], v[84:85], v[226:227]
	v_pk_mul_f32 v[86:87], v[86:87], v[228:229]
	v_pk_mul_f32 v[88:89], v[88:89], v[230:231]
	v_pk_mul_f32 v[90:91], v[90:91], v[232:233]
	v_pk_mul_f32 v[92:93], v[92:93], v[234:235]
	v_pk_mul_f32 v[94:95], v[94:95], v[236:237]
	v_pk_mul_f32 v[96:97], v[96:97], v[238:239]
	v_pk_mul_f32 v[66:67], v[66:67], v[224:225]
	v_pk_mul_f32 v[68:69], v[68:69], v[226:227]
	v_pk_mul_f32 v[70:71], v[70:71], v[228:229]
	v_pk_mul_f32 v[72:73], v[72:73], v[230:231]
	v_pk_mul_f32 v[74:75], v[74:75], v[232:233]
	v_pk_mul_f32 v[76:77], v[76:77], v[234:235]
	v_pk_mul_f32 v[78:79], v[78:79], v[236:237]
	v_pk_mul_f32 v[80:81], v[80:81], v[238:239]
	v_pk_mul_f32 v[50:51], v[50:51], v[224:225]
	v_pk_mul_f32 v[52:53], v[52:53], v[226:227]
	v_pk_mul_f32 v[54:55], v[54:55], v[228:229]
	v_pk_mul_f32 v[56:57], v[56:57], v[230:231]
	v_pk_mul_f32 v[58:59], v[58:59], v[232:233]
	v_pk_mul_f32 v[60:61], v[60:61], v[234:235]
	v_pk_mul_f32 v[62:63], v[62:63], v[236:237]
	v_pk_mul_f32 v[64:65], v[64:65], v[238:239]
	v_pk_mul_f32 v[34:35], v[34:35], v[224:225]
	v_pk_mul_f32 v[36:37], v[36:37], v[226:227]
	v_pk_mul_f32 v[38:39], v[38:39], v[228:229]
	v_pk_mul_f32 v[40:41], v[40:41], v[230:231]
	v_pk_mul_f32 v[42:43], v[42:43], v[232:233]
	v_pk_mul_f32 v[44:45], v[44:45], v[234:235]
	v_pk_mul_f32 v[46:47], v[46:47], v[236:237]
	v_pk_mul_f32 v[48:49], v[48:49], v[238:239]
	v_pk_mul_f32 v[18:19], v[18:19], v[224:225]
	v_pk_mul_f32 v[20:21], v[20:21], v[226:227]
	v_pk_mul_f32 v[22:23], v[22:23], v[228:229]
	v_pk_mul_f32 v[24:25], v[24:25], v[230:231]
	v_pk_mul_f32 v[26:27], v[26:27], v[232:233]
	v_pk_mul_f32 v[28:29], v[28:29], v[234:235]
	v_pk_mul_f32 v[30:31], v[30:31], v[236:237]
	v_pk_mul_f32 v[32:33], v[32:33], v[238:239]
	v_pk_mul_f32 v[2:3], v[2:3], v[224:225]
	v_pk_mul_f32 v[4:5], v[4:5], v[226:227]
	v_pk_mul_f32 v[6:7], v[6:7], v[228:229]
	v_pk_mul_f32 v[8:9], v[8:9], v[230:231]
	v_pk_mul_f32 v[10:11], v[10:11], v[232:233]
	v_pk_mul_f32 v[12:13], v[12:13], v[234:235]
	v_pk_mul_f32 v[14:15], v[14:15], v[236:237]
	v_pk_mul_f32 v[16:17], v[16:17], v[238:239]
	ds_read_b64_tr_b16 v[244:245], v221 offset:0x0
	ds_read_b64_tr_b16 v[246:247], v221 offset:0x800
	ds_read_b64_tr_b16 v[248:249], v221 offset:0x200
	ds_read_b64_tr_b16 v[250:251], v221 offset:0xa00
	ds_read_b64_tr_b16 v[224:225], v221 offset:0x400
	ds_read_b64_tr_b16 v[226:227], v221 offset:0xc00
	ds_read_b64_tr_b16 v[228:229], v221 offset:0x600
	ds_read_b64_tr_b16 v[230:231], v221 offset:0xe00
	ds_read_b64_tr_b16 v[232:233], v221 offset:0x4000
	ds_read_b64_tr_b16 v[234:235], v221 offset:0x4800
	ds_read_b64_tr_b16 v[236:237], v221 offset:0x4200
	ds_read_b64_tr_b16 v[238:239], v221 offset:0x4a00
	s_branch .Lattn_resc_done_b0
; __device__ __forceinline__ int crow(int r, int hi) { return (r & 3) + 8 * (r >> 2) + 4 * hi; }
; template <int LDQ, int LDK, int LDV, int LDO>
; __device__ __forceinline__ void attn256_body(const int tid, const bf16_t* __restrict__ Qb, const bf16_t* __restrict__ Kh, const bf16_t* __restrict__ Vh, bf16_t* __restrict__ Ob, int seq, char* lds, LAS unsigned char* ldsl) {
;     ...
;         if (__any(alpha < 1.f)) { if (hi == 0) al_l[r32] = alpha; asm volatile("s_waitcnt lgkmcnt(0)" ::: "memory");
; #pragma unroll
;             for (int r = 0; r < 16; ++r) { const float f = al_l[crow(r, hi)];
; #pragma unroll
;                 for (int d = 0; d < 8; ++d) o[d][r] *= f; } }
.Lattn_rescale_b1:
	s_and_saveexec_b64 vcc, s[4:5]
	ds_write_b32 v217, v243 offset:128
	s_or_b64 exec, exec, vcc
	s_waitcnt lgkmcnt(0)
	v_add_u32_e32 v240, s17, v194
	ds_read_b128 v[224:227], v240 offset:128
	ds_read_b128 v[228:231], v240 offset:160
	ds_read_b128 v[232:235], v240 offset:192
	ds_read_b128 v[236:239], v240 offset:224
	s_waitcnt lgkmcnt(0)
	v_pk_mul_f32 v[114:115], v[114:115], v[224:225]
	v_pk_mul_f32 v[116:117], v[116:117], v[226:227]
	v_pk_mul_f32 v[118:119], v[118:119], v[228:229]
	v_pk_mul_f32 v[120:121], v[120:121], v[230:231]
	v_pk_mul_f32 v[122:123], v[122:123], v[232:233]
	v_pk_mul_f32 v[124:125], v[124:125], v[234:235]
	v_pk_mul_f32 v[126:127], v[126:127], v[236:237]
	v_pk_mul_f32 v[128:129], v[128:129], v[238:239]
	v_pk_mul_f32 v[98:99], v[98:99], v[224:225]
	v_pk_mul_f32 v[100:101], v[100:101], v[226:227]
	v_pk_mul_f32 v[102:103], v[102:103], v[228:229]
	v_pk_mul_f32 v[104:105], v[104:105], v[230:231]
	v_pk_mul_f32 v[106:107], v[106:107], v[232:233]
	v_pk_mul_f32 v[108:109], v[108:109], v[234:235]
	v_pk_mul_f32 v[110:111], v[110:111], v[236:237]
	v_pk_mul_f32 v[112:113], v[112:113], v[238:239]
	v_pk_mul_f32 v[82:83], v[82:83], v[224:225]
	v_pk_mul_f32 v[84:85], v[84:85], v[226:227]
	v_pk_mul_f32 v[86:87], v[86:87], v[228:229]
	v_pk_mul_f32 v[88:89], v[88:89], v[230:231]
	v_pk_mul_f32 v[90:91], v[90:91], v[232:233]
	v_pk_mul_f32 v[92:93], v[92:93], v[234:235]
	v_pk_mul_f32 v[94:95], v[94:95], v[236:237]
	v_pk_mul_f32 v[96:97], v[96:97], v[238:239]
	v_pk_mul_f32 v[66:67], v[66:67], v[224:225]
	v_pk_mul_f32 v[68:69], v[68:69], v[226:227]
	v_pk_mul_f32 v[70:71], v[70:71], v[228:229]
	v_pk_mul_f32 v[72:73], v[72:73], v[230:231]
	v_pk_mul_f32 v[74:75], v[74:75], v[232:233]
	v_pk_mul_f32 v[76:77], v[76:77], v[234:235]
	v_pk_mul_f32 v[78:79], v[78:79], v[236:237]
	v_pk_mul_f32 v[80:81], v[80:81], v[238:239]
	v_pk_mul_f32 v[50:51], v[50:51], v[224:225]
	v_pk_mul_f32 v[52:53], v[52:53], v[226:227]
	v_pk_mul_f32 v[54:55], v[54:55], v[228:229]
	v_pk_mul_f32 v[56:57], v[56:57], v[230:231]
	v_pk_mul_f32 v[58:59], v[58:59], v[232:233]
	v_pk_mul_f32 v[60:61], v[60:61], v[234:235]
	v_pk_mul_f32 v[62:63], v[62:63], v[236:237]
	v_pk_mul_f32 v[64:65], v[64:65], v[238:239]
	v_pk_mul_f32 v[34:35], v[34:35], v[224:225]
	v_pk_mul_f32 v[36:37], v[36:37], v[226:227]
	v_pk_mul_f32 v[38:39], v[38:39], v[228:229]
	v_pk_mul_f32 v[40:41], v[40:41], v[230:231]
	v_pk_mul_f32 v[42:43], v[42:43], v[232:233]
	v_pk_mul_f32 v[44:45], v[44:45], v[234:235]
	v_pk_mul_f32 v[46:47], v[46:47], v[236:237]
	v_pk_mul_f32 v[48:49], v[48:49], v[238:239]
	v_pk_mul_f32 v[18:19], v[18:19], v[224:225]
	v_pk_mul_f32 v[20:21], v[20:21], v[226:227]
	v_pk_mul_f32 v[22:23], v[22:23], v[228:229]
	v_pk_mul_f32 v[24:25], v[24:25], v[230:231]
	v_pk_mul_f32 v[26:27], v[26:27], v[232:233]
	v_pk_mul_f32 v[28:29], v[28:29], v[234:235]
	v_pk_mul_f32 v[30:31], v[30:31], v[236:237]
	v_pk_mul_f32 v[32:33], v[32:33], v[238:239]
	v_pk_mul_f32 v[2:3], v[2:3], v[224:225]
	v_pk_mul_f32 v[4:5], v[4:5], v[226:227]
	v_pk_mul_f32 v[6:7], v[6:7], v[228:229]
	v_pk_mul_f32 v[8:9], v[8:9], v[230:231]
	v_pk_mul_f32 v[10:11], v[10:11], v[232:233]
	v_pk_mul_f32 v[12:13], v[12:13], v[234:235]
	v_pk_mul_f32 v[14:15], v[14:15], v[236:237]
	v_pk_mul_f32 v[16:17], v[16:17], v[238:239]
	ds_read_b64_tr_b16 v[244:245], v221 offset:0x8000
	ds_read_b64_tr_b16 v[246:247], v221 offset:0x8800
	ds_read_b64_tr_b16 v[248:249], v221 offset:0x8200
	ds_read_b64_tr_b16 v[250:251], v221 offset:0x8a00
	ds_read_b64_tr_b16 v[224:225], v221 offset:0x8400
	ds_read_b64_tr_b16 v[226:227], v221 offset:0x8c00
	ds_read_b64_tr_b16 v[228:229], v221 offset:0x8600
	ds_read_b64_tr_b16 v[230:231], v221 offset:0x8e00
	ds_read_b64_tr_b16 v[232:233], v221 offset:0xc000
	ds_read_b64_tr_b16 v[234:235], v221 offset:0xc800
	ds_read_b64_tr_b16 v[236:237], v221 offset:0xc200
	ds_read_b64_tr_b16 v[238:239], v221 offset:0xca00
	s_branch .Lattn_resc_done_b1
